# grid-wide P3 completion now checked per wave at the start of the out-projection epilogue (before the first X116 store) instead of at the GroupNorm panel wait
# baseline (speedup 1.0000x reference)
; #define PG8_STAGE(bufoff, gbase, voff) do { _Pragma("unroll") for (int _i = 0; _i < 2; ++_i) \
;         __builtin_amdgcn_global_load_lds((const unsigned*)((const char*)(gbase) + (voff)[_i]), (LAS unsigned*)(lds + (bufoff) + ldsw + _i * 8192), 16, 0, 0); } while (0)
; #define PG8_LDA(dst, b, h) do { _Pragma("unroll") for (int m = 0; m < 4; ++m) _Pragma("unroll") for (int k = 0; k < 2; ++k) dst[m][k] = *(const LAS h16x8*)(lds + PG8_SA(b, h) + aoff + m * 2048 + k * 1024); } while (0)
; #define PG8_WAIT_V(n) asm volatile("s_waitcnt vmcnt(" #n ")" ::: "memory")
; #define PG8_WAIT_L(n) asm volatile("s_waitcnt lgkmcnt(" #n ")" ::: "memory")
; template <class Epi>
; __device__ __forceinline__ void gemm_phase(LAS unsigned char* lds, const Gemm g, const StaticOrder& S, const Epi& E) {
;     ...
;         for (int t = 0; t < nt; t += 2) {
;             const bool last = (t == nt - 2);
;             const char* a1 = cA + (size_t)(t + 1) * kstep;
;             const char* a2 = last ? nA : cA + (size_t)(t + 2) * kstep; const char* b2 = last ? nB : cB + (size_t)(t + 2) * kstep;
;             const char* a3 = a2 + kstep; const char* b3 = b2 + kstep;
;             PG8_LDB(B0, 0, 0); PG8_SCHED; PG8_LDA(At, 0, 0); PG8_STAGE(PG8_SA(1, 1), a1 + hstep, voffA);
;             PG8_WAIT_L(8); PG8_BAR; PG8_WAIT_L(0); PG8_MMA(0, 0, At, B0); PG8_BAR; PG8_SCHED;
;             PG8_LDB(B1, 0, 1); PG8_STAGE(PG8_SB(0, 0), b2, voffB);
;             PG8_BAR; PG8_WAIT_L(0); PG8_MMA(0, 1, At, B1); PG8_BAR;
;             PG8_LDA(At, 0, 1); PG8_STAGE(PG8_SA(0, 0), a2, voffA);
;             PG8_BAR; PG8_WAIT_L(0); PG8_MMA(1, 0, At, B0); PG8_BAR; PG8_SCHED;
;             PG8_STAGE(PG8_SB(0, 1), b2 + hstep, voffB);
;             PG8_WAIT_V(6); PG8_BAR; PG8_MMA(1, 1, At, B1); PG8_BAR;
;             PG8_LDB(B0, 1, 0); PG8_SCHED; PG8_LDA(At, 1, 0); PG8_STAGE(PG8_SA(0, 1), a2 + hstep, voffA);
;             PG8_WAIT_L(8); PG8_BAR; PG8_WAIT_L(0); PG8_MMA(0, 0, At, B0); PG8_BAR; PG8_SCHED;
;             PG8_LDB(B1, 1, 1); PG8_STAGE(PG8_SB(1, 0), b3, voffB);
;             PG8_BAR; PG8_WAIT_L(0); PG8_MMA(0, 1, At, B1); PG8_BAR;
;             PG8_LDA(At, 1, 1); PG8_STAGE(PG8_SA(1, 0), a3, voffA);
;             PG8_BAR; PG8_WAIT_L(0); PG8_MMA(1, 0, At, B0); PG8_BAR; PG8_SCHED;
;             PG8_STAGE(PG8_SB(1, 1), b3 + hstep, voffB);
;             PG8_WAIT_V(6); PG8_BAR; PG8_MMA(1, 1, At, B1); PG8_BAR;
.LBB0_422:
	ds_read_b128 v[162:165], v145
	ds_read_b128 v[168:171], v145 offset:1024
	ds_read_b128 v[172:175], v145 offset:2048
	ds_read_b128 v[176:179], v145 offset:3072
	s_add_u32 s28, s26, 0xfffc0080
	s_addc_u32 s29, s27, -1
	s_cmp_eq_u32 s50, 12
	s_cselect_b32 s31, s17, s29
	s_cselect_b32 s30, s23, s28
	s_cselect_b32 s29, s13, s49
	s_cselect_b32 s28, s47, s48
	v_lshl_add_u64 v[212:213], s[26:27], 0, v[154:155]
	s_add_i32 m0, s25, 0xc000
	ds_read_b128 v[180:183], v147
	ds_read_b128 v[184:187], v147 offset:1024
	ds_read_b128 v[188:191], v147 offset:2048
	ds_read_b128 v[192:195], v147 offset:3072
	ds_read_b128 v[196:199], v147 offset:4096
	ds_read_b128 v[200:203], v147 offset:5120
	ds_read_b128 v[204:207], v147 offset:6144
	ds_read_b128 v[208:211], v147 offset:7168
	global_load_lds_dwordx4 v[212:213], off
	v_lshl_add_u64 v[212:213], s[26:27], 0, v[156:157]
	s_add_i32 m0, s25, 0xe000
	s_nop 0
	global_load_lds_dwordx4 v[212:213], off
	s_waitcnt lgkmcnt(8)
	s_barrier
	s_waitcnt lgkmcnt(0)
	s_setprio 1
	s_waitcnt lgkmcnt(0)
	v_mfma_f32_16x16x32_f16 v[124:127], v[162:165], v[180:183], v[124:127]
	v_mfma_f32_16x16x32_f16 v[120:123], v[172:175], v[180:183], v[120:123]
	v_mfma_f32_16x16x32_f16 v[108:111], v[162:165], v[188:191], v[108:111]
	v_mfma_f32_16x16x32_f16 v[104:107], v[172:175], v[188:191], v[104:107]
	v_mfma_f32_16x16x32_f16 v[92:95], v[162:165], v[196:199], v[92:95]
	v_mfma_f32_16x16x32_f16 v[88:91], v[172:175], v[196:199], v[88:91]
	v_mfma_f32_16x16x32_f16 v[76:79], v[162:165], v[204:207], v[76:79]
	v_mfma_f32_16x16x32_f16 v[72:75], v[172:175], v[204:207], v[72:75]
	v_mfma_f32_16x16x32_f16 v[124:127], v[168:171], v[184:187], v[124:127]
	v_mfma_f32_16x16x32_f16 v[120:123], v[176:179], v[184:187], v[120:123]
	v_mfma_f32_16x16x32_f16 v[108:111], v[168:171], v[192:195], v[108:111]
	v_mfma_f32_16x16x32_f16 v[104:107], v[176:179], v[192:195], v[104:107]
	v_mfma_f32_16x16x32_f16 v[92:95], v[168:171], v[200:203], v[92:95]
	v_mfma_f32_16x16x32_f16 v[88:91], v[176:179], v[200:203], v[88:91]
	v_mfma_f32_16x16x32_f16 v[76:79], v[168:171], v[208:211], v[76:79]
	v_mfma_f32_16x16x32_f16 v[72:75], v[176:179], v[208:211], v[72:75]
	s_setprio 0
	s_barrier
	s_add_i32 s51, s45, s37
	v_lshl_add_u64 v[228:229], s[28:29], 0, v[148:149]
	s_mov_b32 m0, s51
	ds_read_b128 v[212:215], v166
	ds_read_b128 v[216:219], v166 offset:1024
	ds_read_b128 v[220:223], v166 offset:2048
	ds_read_b128 v[224:227], v166 offset:3072
	global_load_lds_dwordx4 v[228:229], off
	v_lshl_add_u64 v[230:231], s[28:29], 0, v[152:153]
	s_add_i32 m0, s51, 0x2000
	s_nop 0
	global_load_lds_dwordx4 v[230:231], off
	s_barrier
	s_waitcnt lgkmcnt(0)
	s_setprio 1
	s_waitcnt lgkmcnt(0)
	v_mfma_f32_16x16x32_f16 v[116:119], v[212:215], v[180:183], v[116:119]
	v_mfma_f32_16x16x32_f16 v[112:115], v[220:223], v[180:183], v[112:115]
	v_mfma_f32_16x16x32_f16 v[100:103], v[212:215], v[188:191], v[100:103]
	v_mfma_f32_16x16x32_f16 v[96:99], v[220:223], v[188:191], v[96:99]
	v_mfma_f32_16x16x32_f16 v[84:87], v[212:215], v[196:199], v[84:87]
	v_mfma_f32_16x16x32_f16 v[80:83], v[220:223], v[196:199], v[80:83]
	v_mfma_f32_16x16x32_f16 v[68:71], v[212:215], v[204:207], v[68:71]
	v_mfma_f32_16x16x32_f16 v[64:67], v[220:223], v[204:207], v[64:67]
	v_mfma_f32_16x16x32_f16 v[116:119], v[216:219], v[184:187], v[116:119]
	v_mfma_f32_16x16x32_f16 v[112:115], v[224:227], v[184:187], v[112:115]
	v_mfma_f32_16x16x32_f16 v[100:103], v[216:219], v[192:195], v[100:103]
	v_mfma_f32_16x16x32_f16 v[96:99], v[224:227], v[192:195], v[96:99]
	v_mfma_f32_16x16x32_f16 v[84:87], v[216:219], v[200:203], v[84:87]
	v_mfma_f32_16x16x32_f16 v[80:83], v[224:227], v[200:203], v[80:83]
	v_mfma_f32_16x16x32_f16 v[68:71], v[216:219], v[208:211], v[68:71]
	v_mfma_f32_16x16x32_f16 v[64:67], v[224:227], v[208:211], v[64:67]
	s_setprio 0
	s_mov_b32 m0, s25
	v_lshl_add_u64 v[232:233], s[30:31], 0, v[142:143]
	s_barrier
	ds_read_b128 v[180:183], v147 offset:16384
	ds_read_b128 v[184:187], v147 offset:17408
	ds_read_b128 v[188:191], v147 offset:18432
	ds_read_b128 v[192:195], v147 offset:19456
	ds_read_b128 v[196:199], v147 offset:20480
	ds_read_b128 v[200:203], v147 offset:21504
	ds_read_b128 v[204:207], v147 offset:22528
	ds_read_b128 v[208:211], v147 offset:23552
	global_load_lds_dwordx4 v[232:233], off
	v_lshl_add_u64 v[234:235], s[30:31], 0, v[150:151]
	s_mov_b32 m0, s38
	s_nop 0
	global_load_lds_dwordx4 v[234:235], off
	s_barrier
	s_waitcnt lgkmcnt(0)
	s_setprio 1
	s_waitcnt lgkmcnt(0)
	v_mfma_f32_16x16x32_f16 v[60:63], v[162:165], v[180:183], v[60:63]
	v_mfma_f32_16x16x32_f16 v[56:59], v[172:175], v[180:183], v[56:59]
	v_mfma_f32_16x16x32_f16 v[44:47], v[162:165], v[188:191], v[44:47]
	v_mfma_f32_16x16x32_f16 v[40:43], v[172:175], v[188:191], v[40:43]
	v_mfma_f32_16x16x32_f16 v[28:31], v[162:165], v[196:199], v[28:31]
	v_mfma_f32_16x16x32_f16 v[24:27], v[172:175], v[196:199], v[24:27]
	v_mfma_f32_16x16x32_f16 v[12:15], v[162:165], v[204:207], v[12:15]
	v_mfma_f32_16x16x32_f16 v[8:11], v[172:175], v[204:207], v[8:11]
	v_mfma_f32_16x16x32_f16 v[60:63], v[168:171], v[184:187], v[60:63]
	v_mfma_f32_16x16x32_f16 v[56:59], v[176:179], v[184:187], v[56:59]
	v_mfma_f32_16x16x32_f16 v[44:47], v[168:171], v[192:195], v[44:47]
	v_mfma_f32_16x16x32_f16 v[40:43], v[176:179], v[192:195], v[40:43]
	v_mfma_f32_16x16x32_f16 v[28:31], v[168:171], v[200:203], v[28:31]
	v_mfma_f32_16x16x32_f16 v[24:27], v[176:179], v[200:203], v[24:27]
	v_mfma_f32_16x16x32_f16 v[12:15], v[168:171], v[208:211], v[12:15]
	v_mfma_f32_16x16x32_f16 v[8:11], v[176:179], v[208:211], v[8:11]
	s_setprio 0
	s_barrier
; #define PG8_STAGE(bufoff, gbase, voff) do { _Pragma("unroll") for (int _i = 0; _i < 2; ++_i) \
;         __builtin_amdgcn_global_load_lds((const unsigned*)((const char*)(gbase) + (voff)[_i]), (LAS unsigned*)(lds + (bufoff) + ldsw + _i * 8192), 16, 0, 0); } while (0)
; #define PG8_LDA(dst, b, h) do { _Pragma("unroll") for (int m = 0; m < 4; ++m) _Pragma("unroll") for (int k = 0; k < 2; ++k) dst[m][k] = *(const LAS h16x8*)(lds + PG8_SA(b, h) + aoff + m * 2048 + k * 1024); } while (0)
; #define PG8_WAIT_V(n) asm volatile("s_waitcnt vmcnt(" #n ")" ::: "memory")
; #define PG8_WAIT_L(n) asm volatile("s_waitcnt lgkmcnt(" #n ")" ::: "memory")
; template <class Epi>
; __device__ __forceinline__ void gemm_phase(LAS unsigned char* lds, const Gemm g, const StaticOrder& S, const Epi& E) {
;     ...
;         for (int t = 0; t < nt; t += 2) {
;             const bool last = (t == nt - 2);
;             const char* a1 = cA + (size_t)(t + 1) * kstep;
;             const char* a2 = last ? nA : cA + (size_t)(t + 2) * kstep; const char* b2 = last ? nB : cB + (size_t)(t + 2) * kstep;
;             const char* a3 = a2 + kstep; const char* b3 = b2 + kstep;
;             PG8_LDB(B0, 0, 0); PG8_SCHED; PG8_LDA(At, 0, 0); PG8_STAGE(PG8_SA(1, 1), a1 + hstep, voffA);
;             PG8_WAIT_L(8); PG8_BAR; PG8_WAIT_L(0); PG8_MMA(0, 0, At, B0); PG8_BAR; PG8_SCHED;
;             PG8_LDB(B1, 0, 1); PG8_STAGE(PG8_SB(0, 0), b2, voffB);
;             PG8_BAR; PG8_WAIT_L(0); PG8_MMA(0, 1, At, B1); PG8_BAR;
;             PG8_LDA(At, 0, 1); PG8_STAGE(PG8_SA(0, 0), a2, voffA);
;             PG8_BAR; PG8_WAIT_L(0); PG8_MMA(1, 0, At, B0); PG8_BAR; PG8_SCHED;
;             PG8_STAGE(PG8_SB(0, 1), b2 + hstep, voffB);
;             PG8_WAIT_V(6); PG8_BAR; PG8_MMA(1, 1, At, B1); PG8_BAR;
;             PG8_LDB(B0, 1, 0); PG8_SCHED; PG8_LDA(At, 1, 0); PG8_STAGE(PG8_SA(0, 1), a2 + hstep, voffA);
;             PG8_WAIT_L(8); PG8_BAR; PG8_WAIT_L(0); PG8_MMA(0, 0, At, B0); PG8_BAR; PG8_SCHED;
;             PG8_LDB(B1, 1, 1); PG8_STAGE(PG8_SB(1, 0), b3, voffB);
;             PG8_BAR; PG8_WAIT_L(0); PG8_MMA(0, 1, At, B1); PG8_BAR;
;             PG8_LDA(At, 1, 1); PG8_STAGE(PG8_SA(1, 0), a3, voffA);
;             PG8_BAR; PG8_WAIT_L(0); PG8_MMA(1, 0, At, B0); PG8_BAR; PG8_SCHED;
;             PG8_STAGE(PG8_SB(1, 1), b3 + hstep, voffB);
;             PG8_WAIT_V(6); PG8_BAR; PG8_MMA(1, 1, At, B1); PG8_BAR;
	s_add_u32 s52, s28, 0x40000
	s_addc_u32 s53, s29, 0
	s_add_i32 s51, s46, s37
	v_lshl_add_u64 v[162:163], s[52:53], 0, v[148:149]
	s_mov_b32 m0, s51
	s_nop 0
	global_load_lds_dwordx4 v[162:163], off
	v_lshl_add_u64 v[162:163], s[52:53], 0, v[152:153]
	s_add_i32 m0, s51, 0x2000
	s_nop 0
	global_load_lds_dwordx4 v[162:163], off
	s_waitcnt vmcnt(6)
	s_barrier
	s_setprio 1
	v_mfma_f32_16x16x32_f16 v[52:55], v[212:215], v[180:183], v[52:55]
	v_mfma_f32_16x16x32_f16 v[48:51], v[220:223], v[180:183], v[48:51]
	v_mfma_f32_16x16x32_f16 v[36:39], v[212:215], v[188:191], v[36:39]
	v_mfma_f32_16x16x32_f16 v[32:35], v[220:223], v[188:191], v[32:35]
	v_mfma_f32_16x16x32_f16 v[20:23], v[212:215], v[196:199], v[20:23]
	v_mfma_f32_16x16x32_f16 v[16:19], v[220:223], v[196:199], v[16:19]
	v_mfma_f32_16x16x32_f16 v[4:7], v[212:215], v[204:207], v[4:7]
	v_mfma_f32_16x16x32_f16 v[0:3], v[220:223], v[204:207], v[0:3]
	v_mfma_f32_16x16x32_f16 v[52:55], v[216:219], v[184:187], v[52:55]
	v_mfma_f32_16x16x32_f16 v[48:51], v[224:227], v[184:187], v[48:51]
	v_mfma_f32_16x16x32_f16 v[36:39], v[216:219], v[192:195], v[36:39]
	v_mfma_f32_16x16x32_f16 v[32:35], v[224:227], v[192:195], v[32:35]
	v_mfma_f32_16x16x32_f16 v[20:23], v[216:219], v[200:203], v[20:23]
	v_mfma_f32_16x16x32_f16 v[16:19], v[224:227], v[200:203], v[16:19]
	v_mfma_f32_16x16x32_f16 v[4:7], v[216:219], v[208:211], v[4:7]
	v_mfma_f32_16x16x32_f16 v[0:3], v[224:227], v[208:211], v[0:3]
	s_setprio 0
	s_add_i32 s51, 0, 0x18000
	v_add_u32_e32 v167, s51, v139
	s_barrier
	ds_read_b128 v[162:165], v167
	ds_read_b128 v[168:171], v167 offset:1024
	ds_read_b128 v[172:175], v167 offset:2048
	ds_read_b128 v[176:179], v167 offset:3072
	s_add_u32 s30, s30, 0x40000
	s_addc_u32 s31, s31, 0
	s_mov_b32 m0, s39
	v_lshl_add_u64 v[212:213], s[30:31], 0, v[142:143]
	ds_read_b128 v[180:183], v147 offset:32768
	ds_read_b128 v[184:187], v147 offset:33792
	ds_read_b128 v[188:191], v147 offset:34816
	ds_read_b128 v[192:195], v147 offset:35840
	ds_read_b128 v[196:199], v147 offset:36864
	ds_read_b128 v[200:203], v147 offset:37888
	ds_read_b128 v[204:207], v147 offset:38912
	ds_read_b128 v[208:211], v147 offset:39936
	global_load_lds_dwordx4 v[212:213], off
	v_lshl_add_u64 v[212:213], s[30:31], 0, v[150:151]
	s_mov_b32 m0, s41
	s_nop 0
	global_load_lds_dwordx4 v[212:213], off
	s_waitcnt lgkmcnt(8)
	s_barrier
	s_waitcnt lgkmcnt(0)
	s_setprio 1
	s_waitcnt lgkmcnt(0)
	v_mfma_f32_16x16x32_f16 v[124:127], v[162:165], v[180:183], v[124:127]
	v_mfma_f32_16x16x32_f16 v[120:123], v[172:175], v[180:183], v[120:123]
	v_mfma_f32_16x16x32_f16 v[108:111], v[162:165], v[188:191], v[108:111]
	v_mfma_f32_16x16x32_f16 v[104:107], v[172:175], v[188:191], v[104:107]
	v_mfma_f32_16x16x32_f16 v[92:95], v[162:165], v[196:199], v[92:95]
	v_mfma_f32_16x16x32_f16 v[88:91], v[172:175], v[196:199], v[88:91]
	v_mfma_f32_16x16x32_f16 v[76:79], v[162:165], v[204:207], v[76:79]
	v_mfma_f32_16x16x32_f16 v[72:75], v[172:175], v[204:207], v[72:75]
	v_mfma_f32_16x16x32_f16 v[124:127], v[168:171], v[184:187], v[124:127]
	v_mfma_f32_16x16x32_f16 v[120:123], v[176:179], v[184:187], v[120:123]
	v_mfma_f32_16x16x32_f16 v[108:111], v[168:171], v[192:195], v[108:111]
	v_mfma_f32_16x16x32_f16 v[104:107], v[176:179], v[192:195], v[104:107]
	v_mfma_f32_16x16x32_f16 v[92:95], v[168:171], v[200:203], v[92:95]
	v_mfma_f32_16x16x32_f16 v[88:91], v[176:179], v[200:203], v[88:91]
	v_mfma_f32_16x16x32_f16 v[76:79], v[168:171], v[208:211], v[76:79]
	v_mfma_f32_16x16x32_f16 v[72:75], v[176:179], v[208:211], v[72:75]
	s_setprio 0
	s_barrier
	s_add_i32 s30, 0, 0x1c000
	s_add_i32 s31, s51, s37
	v_add_u32_e32 v167, s30, v139
	v_lshl_add_u64 v[228:229], v[228:229], 0, s[0:1]
	s_mov_b32 m0, s31
	ds_read_b128 v[212:215], v167
	ds_read_b128 v[216:219], v167 offset:1024
	ds_read_b128 v[220:223], v167 offset:2048
	ds_read_b128 v[224:227], v167 offset:3072
	global_load_lds_dwordx4 v[228:229], off
	v_lshl_add_u64 v[228:229], v[230:231], 0, s[0:1]
	s_add_i32 m0, s31, 0x2000
	s_nop 0
	global_load_lds_dwordx4 v[228:229], off
	s_barrier
	s_waitcnt lgkmcnt(0)
	s_setprio 1
	s_waitcnt lgkmcnt(0)
	v_mfma_f32_16x16x32_f16 v[116:119], v[212:215], v[180:183], v[116:119]
	v_mfma_f32_16x16x32_f16 v[112:115], v[220:223], v[180:183], v[112:115]
	v_mfma_f32_16x16x32_f16 v[100:103], v[212:215], v[188:191], v[100:103]
	v_mfma_f32_16x16x32_f16 v[96:99], v[220:223], v[188:191], v[96:99]
	v_mfma_f32_16x16x32_f16 v[84:87], v[212:215], v[196:199], v[84:87]
	v_mfma_f32_16x16x32_f16 v[80:83], v[220:223], v[196:199], v[80:83]
	v_mfma_f32_16x16x32_f16 v[68:71], v[212:215], v[204:207], v[68:71]
	v_mfma_f32_16x16x32_f16 v[64:67], v[220:223], v[204:207], v[64:67]
	v_mfma_f32_16x16x32_f16 v[116:119], v[216:219], v[184:187], v[116:119]
	v_mfma_f32_16x16x32_f16 v[112:115], v[224:227], v[184:187], v[112:115]
	v_mfma_f32_16x16x32_f16 v[100:103], v[216:219], v[192:195], v[100:103]
	v_mfma_f32_16x16x32_f16 v[96:99], v[224:227], v[192:195], v[96:99]
	v_mfma_f32_16x16x32_f16 v[84:87], v[216:219], v[200:203], v[84:87]
	v_mfma_f32_16x16x32_f16 v[80:83], v[224:227], v[200:203], v[80:83]
	v_mfma_f32_16x16x32_f16 v[68:71], v[216:219], v[208:211], v[68:71]
	v_mfma_f32_16x16x32_f16 v[64:67], v[224:227], v[208:211], v[64:67]
	s_setprio 0
	s_mov_b32 m0, s43
	v_lshl_add_u64 v[228:229], v[232:233], 0, s[0:1]
	s_barrier
	ds_read_b128 v[180:183], v147 offset:49152
	ds_read_b128 v[184:187], v147 offset:50176
	ds_read_b128 v[188:191], v147 offset:51200
	ds_read_b128 v[192:195], v147 offset:52224
	ds_read_b128 v[196:199], v147 offset:53248
	ds_read_b128 v[200:203], v147 offset:54272
	ds_read_b128 v[204:207], v147 offset:55296
	ds_read_b128 v[208:211], v147 offset:56320
	global_load_lds_dwordx4 v[228:229], off
	v_lshl_add_u64 v[228:229], v[234:235], 0, s[0:1]
	s_mov_b32 m0, s44
	s_nop 0
	global_load_lds_dwordx4 v[228:229], off
	s_barrier
; #define PG8_STAGE(bufoff, gbase, voff) do { _Pragma("unroll") for (int _i = 0; _i < 2; ++_i) \
;         __builtin_amdgcn_global_load_lds((const unsigned*)((const char*)(gbase) + (voff)[_i]), (LAS unsigned*)(lds + (bufoff) + ldsw + _i * 8192), 16, 0, 0); } while (0)
; #define PG8_LDA(dst, b, h) do { _Pragma("unroll") for (int m = 0; m < 4; ++m) _Pragma("unroll") for (int k = 0; k < 2; ++k) dst[m][k] = *(const LAS h16x8*)(lds + PG8_SA(b, h) + aoff + m * 2048 + k * 1024); } while (0)
; #define PG8_BAR __builtin_amdgcn_s_barrier()
; template <class Epi>
; __device__ __forceinline__ void gemm_phase(LAS unsigned char* lds, const Gemm g, const StaticOrder& S, const Epi& E) {
;     ...
;             PG8_WAIT_V(6); PG8_BAR; PG8_MMA(1, 1, At, B1); PG8_BAR;
;             PG8_LDB(B0, 1, 0); PG8_SCHED; PG8_LDA(At, 1, 0); PG8_STAGE(PG8_SA(0, 1), a2 + hstep, voffA);
;             PG8_WAIT_L(8); PG8_BAR; PG8_WAIT_L(0); PG8_MMA(0, 0, At, B0); PG8_BAR; PG8_SCHED;
;             PG8_LDB(B1, 1, 1); PG8_STAGE(PG8_SB(1, 0), b3, voffB);
;             PG8_BAR; PG8_WAIT_L(0); PG8_MMA(0, 1, At, B1); PG8_BAR;
;             PG8_LDA(At, 1, 1); PG8_STAGE(PG8_SA(1, 0), a3, voffA);
;             PG8_BAR; PG8_WAIT_L(0); PG8_MMA(1, 0, At, B0); PG8_BAR; PG8_SCHED;
;             PG8_STAGE(PG8_SB(1, 1), b3 + hstep, voffB);
;             PG8_WAIT_V(6); PG8_BAR; PG8_MMA(1, 1, At, B1); PG8_BAR;
;         }
;         if constexpr (!Epi::AFTER_DRAIN) E(acc, cur, wr, wc, fr, fq);
;     __device__ __forceinline__ void operator()(const f32x4 (&acc)[2][2][4][2], const pg8::Unit& u, int wr, int wc, int fr, int fq) const {
;         const int row0 = u.pm * 256 + wr * 64 + fr, col0 = u.pn * 256 + wc * 32 + 8 * fq;
; #pragma unroll
;         for (int ai = 0; ai < 2; ++ai)
; #pragma unroll
;             for (int m = 0; m < 4; ++m) {
;                 const int row = row0 + ai * 128 + m * 16;
;                 float ss = 0.f, rstd = 1.f;
;                 if (MODE == 2) rstd = rsqrtf(rowss[row] * (1.f / 1024.f) + EPS);
; #pragma unroll
;                 for (int bj = 0; bj < 2; ++bj) {
;                     const int c = col0 + bj * 128;
;                     f32x4 v0 = acc[ai][bj][m][0], v1 = acc[ai][bj][m][1];
;                     if (MODE == 1) {
;                         const float* rp = res + (size_t)row * ldres + c;
;                         v0 += *(const f32x4*)rp; v1 += *(const f32x4*)(rp + 4);
	s_waitcnt lgkmcnt(0)
	s_setprio 1
	s_waitcnt lgkmcnt(0)
	v_mfma_f32_16x16x32_f16 v[60:63], v[162:165], v[180:183], v[60:63]
	v_mfma_f32_16x16x32_f16 v[56:59], v[172:175], v[180:183], v[56:59]
	v_mfma_f32_16x16x32_f16 v[44:47], v[162:165], v[188:191], v[44:47]
	v_mfma_f32_16x16x32_f16 v[40:43], v[172:175], v[188:191], v[40:43]
	v_mfma_f32_16x16x32_f16 v[28:31], v[162:165], v[196:199], v[28:31]
	v_mfma_f32_16x16x32_f16 v[24:27], v[172:175], v[196:199], v[24:27]
	v_mfma_f32_16x16x32_f16 v[12:15], v[162:165], v[204:207], v[12:15]
	v_mfma_f32_16x16x32_f16 v[8:11], v[172:175], v[204:207], v[8:11]
	v_mfma_f32_16x16x32_f16 v[60:63], v[168:171], v[184:187], v[60:63]
	v_mfma_f32_16x16x32_f16 v[56:59], v[176:179], v[184:187], v[56:59]
	v_mfma_f32_16x16x32_f16 v[44:47], v[168:171], v[192:195], v[44:47]
	v_mfma_f32_16x16x32_f16 v[40:43], v[176:179], v[192:195], v[40:43]
	v_mfma_f32_16x16x32_f16 v[28:31], v[168:171], v[200:203], v[28:31]
	v_mfma_f32_16x16x32_f16 v[24:27], v[176:179], v[200:203], v[24:27]
	v_mfma_f32_16x16x32_f16 v[12:15], v[168:171], v[208:211], v[12:15]
	v_mfma_f32_16x16x32_f16 v[8:11], v[176:179], v[208:211], v[8:11]
	s_setprio 0
	s_barrier
	s_add_u32 s28, s28, 0x40080
	s_addc_u32 s29, s29, 0
	s_add_i32 s30, s30, s37
	v_lshl_add_u64 v[162:163], s[28:29], 0, v[148:149]
	s_mov_b32 m0, s30
	s_nop 0
	global_load_lds_dwordx4 v[162:163], off
	v_lshl_add_u64 v[162:163], s[28:29], 0, v[152:153]
	s_add_i32 m0, s30, 0x2000
	s_nop 0
	global_load_lds_dwordx4 v[162:163], off
	s_waitcnt vmcnt(6)
	s_barrier
	s_setprio 1
	v_mfma_f32_16x16x32_f16 v[52:55], v[212:215], v[180:183], v[52:55]
	v_mfma_f32_16x16x32_f16 v[48:51], v[220:223], v[180:183], v[48:51]
	v_mfma_f32_16x16x32_f16 v[36:39], v[212:215], v[188:191], v[36:39]
	v_mfma_f32_16x16x32_f16 v[32:35], v[220:223], v[188:191], v[32:35]
	v_mfma_f32_16x16x32_f16 v[20:23], v[212:215], v[196:199], v[20:23]
	v_mfma_f32_16x16x32_f16 v[16:19], v[220:223], v[196:199], v[16:19]
	v_mfma_f32_16x16x32_f16 v[4:7], v[212:215], v[204:207], v[4:7]
	v_mfma_f32_16x16x32_f16 v[0:3], v[220:223], v[204:207], v[0:3]
	v_mfma_f32_16x16x32_f16 v[52:55], v[216:219], v[184:187], v[52:55]
	v_mfma_f32_16x16x32_f16 v[48:51], v[224:227], v[184:187], v[48:51]
	v_mfma_f32_16x16x32_f16 v[36:39], v[216:219], v[192:195], v[36:39]
	v_mfma_f32_16x16x32_f16 v[32:35], v[224:227], v[192:195], v[32:35]
	v_mfma_f32_16x16x32_f16 v[20:23], v[216:219], v[200:203], v[20:23]
	v_mfma_f32_16x16x32_f16 v[16:19], v[224:227], v[200:203], v[16:19]
	v_mfma_f32_16x16x32_f16 v[4:7], v[216:219], v[208:211], v[4:7]
	v_mfma_f32_16x16x32_f16 v[0:3], v[224:227], v[208:211], v[0:3]
	s_setprio 0
	s_add_i32 s50, s50, 2
	s_add_u32 s26, s26, 0x100
	s_addc_u32 s27, s27, 0
	s_add_u32 s48, s48, 0x100
	s_addc_u32 s49, s49, 0
	s_cmp_gt_u32 s50, 13
	s_barrier
	s_cbranch_scc0 .LBB0_422
	v_mov_b32_e32 v206, 0x1b719c0
	global_load_dword v207, v206, s[82:83] sc1
	v_lshl_add_u32 v164, s22, 8, v137
	v_ashrrev_i32_e32 v165, 31, v164
	v_readlane_b32 s48, v253, 4
	v_lshl_or_b32 v162, s24, 8, v141
	v_lshlrev_b64 v[168:169], 12, v[164:165]
	v_readlane_b32 s49, v253, 5
	v_ashrrev_i32_e32 v163, 31, v162
	v_lshlrev_b64 v[178:179], 11, v[164:165]
	v_lshl_add_u64 v[168:169], s[48:49], 0, v[168:169]
	v_lshl_add_u64 v[176:177], v[162:163], 2, v[168:169]
	global_load_dwordx4 v[168:171], v[176:177], off
	global_load_dwordx4 v[172:175], v[176:177], off offset:16
	v_lshlrev_b32_e32 v182, 12, v164
	v_lshl_add_u32 v182, v162, 2, v182
	v_add_u32_e32 v183, 0x80000, v182
	global_load_dword v184, v182, s[48:49] offset:512
	v_add_u32_e32 v185, 0x10000, v182
	global_load_dword v186, v185, s[48:49]
	global_load_dword v187, v185, s[48:49] offset:512
	v_add_u32_e32 v188, 0x20000, v182
	global_load_dword v189, v188, s[48:49]
	global_load_dword v190, v188, s[48:49] offset:512
	v_add_u32_e32 v191, 0x30000, v182
	global_load_dword v192, v191, s[48:49]
	global_load_dword v193, v191, s[48:49] offset:512
	global_load_dword v194, v183, s[48:49]
	global_load_dword v195, v183, s[48:49] offset:512
	v_add_u32_e32 v196, 0x10000, v183
	global_load_dword v197, v196, s[48:49]
	global_load_dword v198, v196, s[48:49] offset:512
	v_add_u32_e32 v199, 0x20000, v183
	global_load_dword v200, v199, s[48:49]
	global_load_dword v201, v199, s[48:49] offset:512
	v_add_u32_e32 v202, 0x30000, v183
	global_load_dword v204, v202, s[48:49]
	global_load_dword v205, v202, s[48:49] offset:512
	v_lshl_add_u64 v[178:179], s[10:11], 0, v[178:179]
	v_lshl_add_u64 v[178:179], v[162:163], 1, v[178:179]
	v_readlane_b32 s50, v253, 6
	v_readlane_b32 s51, v253, 7
	v_readlane_b32 s52, v253, 8
	v_readlane_b32 s53, v253, 9
	v_readlane_b32 s54, v253, 10
	v_readlane_b32 s55, v253, 11
	v_readlane_b32 s56, v253, 12
	v_readlane_b32 s57, v253, 13
	v_readlane_b32 s58, v253, 14
	v_readlane_b32 s59, v253, 15
	v_readlane_b32 s60, v253, 16
	v_readlane_b32 s61, v253, 17
	v_readlane_b32 s62, v253, 18
	v_readlane_b32 s63, v253, 19
	s_waitcnt vmcnt(0)
	s_cmpk_lg_i32 s33, 0x100
	s_cbranch_scc1 .Lps_e_ok
;     __device__ __forceinline__ void operator()(const f32x4 (&acc)[2][2][4][2], const pg8::Unit& u, int wr, int wc, int fr, int fq) const {
;         const int row0 = u.pm * 256 + wr * 64 + fr, col0 = u.pn * 256 + wc * 32 + 8 * fq;
; #pragma unroll
;         for (int ai = 0; ai < 2; ++ai)
; #pragma unroll
;             for (int m = 0; m < 4; ++m) {
;                 const int row = row0 + ai * 128 + m * 16;
;                 float ss = 0.f, rstd = 1.f;
;                 if (MODE == 2) rstd = rsqrtf(rowss[row] * (1.f / 1024.f) + EPS);
; #pragma unroll
;                 for (int bj = 0; bj < 2; ++bj) {
;                     const int c = col0 + bj * 128;
;                     f32x4 v0 = acc[ai][bj][m][0], v1 = acc[ai][bj][m][1];
;                     if (MODE == 1) {
;                         const float* rp = res + (size_t)row * ldres + c;
;                         v0 += *(const f32x4*)rp; v1 += *(const f32x4*)(rp + 4);
;                     }
;                     if (MODE == 3) {
;                         const h16x8 r8 = *(const h16x8*)(res16 + (size_t)row * ldres + c);
; #pragma unroll
;                         for (int j = 0; j < 4; ++j) { v0[j] += (float)r8[j]; v1[j] += (float)r8[4 + j]; }
;                     }
;                     if (MODE == 1 || MODE == 3) {
;                         ss += v0[0] * v0[0] + v0[1] * v0[1] + v0[2] * v0[2] + v0[3] * v0[3] + v1[0] * v1[0] + v1[1] * v1[1] + v1[2] * v1[2] + v1[3] * v1[3];
;                     }
;                     if (MODE == 2) {
; #pragma unroll
;                         for (int j = 0; j < 4; ++j) { float a = fmaxf(v0[j] * rstd, 0.f), b = fmaxf(v1[j] * rstd, 0.f); v0[j] = a * a; v1[j] = b * b; }
;                     }
;                     *(h16x8*)(o16 + (size_t)row * ld16 + c) = pack8(v0, v1);
;                 }
;                 if (MODE == 1 || MODE == 3) {
;                     ss += __shfl_xor(ss, 16); ss += __shfl_xor(ss, 32);
;                     if (fq == 0) atomicAdd(rowss + row, ss);
.Lps_e_chk:
	v_readfirstlane_b32 s97, v207
	s_cmpk_lt_u32 s97, 0x100
	s_cbranch_scc0 .Lps_e_ok
	s_sleep 1
	global_load_dword v207, v206, s[82:83] sc1
	s_waitcnt vmcnt(0)
	s_branch .Lps_e_chk
.Lps_e_ok:
	v_pk_add_f32 v[126:127], v[126:127], v[170:171]
	v_pk_add_f32 v[180:181], v[124:125], v[168:169]
	v_pk_add_f32 v[174:175], v[122:123], v[174:175]
	v_pk_add_f32 v[172:173], v[120:121], v[172:173]
	v_cvt_pk_f16_f32 v123, v174, v175
	v_cvt_pk_f16_f32 v121, v126, v127
	v_cvt_pk_f16_f32 v122, v172, v173
	v_cvt_pk_f16_f32 v120, v180, v181
	global_store_dwordx4 v[178:179], v[120:123], off sc0 sc1
	global_load_dwordx4 v[122:125], v[176:177], off offset:512
	s_nop 0
	global_load_dwordx4 v[168:171], v[176:177], off offset:528
	v_mul_f32_e32 v167, v181, v181
	v_fmac_f32_e32 v167, v180, v180
	v_fmac_f32_e32 v167, v126, v126
	v_fmac_f32_e32 v167, v127, v127
	v_fmac_f32_e32 v167, v172, v172
	v_xor_b32_e32 v120, 16, v129
	v_fmac_f32_e32 v167, v173, v173
	v_cmp_lt_i32_e32 vcc, v120, v135
	v_fmac_f32_e32 v167, v174, v174
	v_fmac_f32_e32 v167, v175, v175
	v_cndmask_b32_e32 v120, v129, v120, vcc
	v_lshlrev_b32_e32 v120, 2, v120
	v_xor_b32_e32 v121, 32, v129
	v_cmp_lt_i32_e32 vcc, v121, v135
	s_waitcnt vmcnt(0)
	v_pk_add_f32 v[122:123], v[116:117], v[122:123]
	v_pk_add_f32 v[126:127], v[112:113], v[168:169]
	v_mul_f32_e32 v112, v123, v123
	v_pk_add_f32 v[124:125], v[118:119], v[124:125]
	v_fmac_f32_e32 v112, v122, v122
	v_fmac_f32_e32 v112, v124, v124
	v_fmac_f32_e32 v112, v125, v125
	v_fmac_f32_e32 v112, v126, v126
	v_pk_add_f32 v[116:117], v[114:115], v[170:171]
	v_fmac_f32_e32 v112, v127, v127
	v_fmac_f32_e32 v112, v116, v116
	v_fmac_f32_e32 v112, v117, v117
	v_add_f32_e32 v112, v167, v112
	v_mov_b32_e32 v113, v112
	s_nop 1
	v_permlane16_swap_b32 v112, v113
	v_cndmask_b32_e32 v114, v129, v121, vcc
	v_lshlrev_b32_e32 v114, 2, v114
	v_cvt_pk_f16_f32 v119, v116, v117
	v_cvt_pk_f16_f32 v117, v124, v125
	s_waitcnt lgkmcnt(0)
	v_add_f32_e32 v112, v112, v113
	v_mov_b32_e32 v113, v112
	s_nop 1
	v_permlane32_swap_b32 v112, v113
	v_cvt_pk_f16_f32 v118, v126, v127
	v_cvt_pk_f16_f32 v116, v122, v123
	global_store_dwordx4 v[178:179], v[116:119], off offset:256 sc0 sc1
	s_and_saveexec_b64 s[22:23], s[6:7]
	s_cbranch_execz .LBB0_425
	v_lshl_add_u64 v[116:117], v[164:165], 2, s[14:15]
	s_waitcnt lgkmcnt(0)
	v_add_f32_e32 v112, v112, v113
	global_atomic_add_f32 v[116:117], v112, off
